# attention: split broadcast v_pk_mul_f32 into 2 v_mul_f32, drop redundant inline-asm s_nop after cvt_pk
# speedup vs baseline: 1.0173x; 1.0007x over previous
.LBB0_295:
	ds_bpermute_b32 v0, v209, v233
	v_lshlrev_b64 v[2:3], 11, v[180:181]
	v_lshl_add_u64 v[2:3], s[94:95], 0, v[2:3]
	v_lshl_add_u64 v[2:3], v[2:3], 0, v[176:177]
	s_mov_b64 s[2:3], 0x9900400
	s_waitcnt lgkmcnt(0)
	v_add_f32_e32 v0, v233, v0
	v_rcp_f32_e32 v8, v0
	s_mov_b32 s0, 0x9900000
	v_readlane_b32 s62, v252, 16
	v_readlane_b32 s64, v253, 22
	v_mul_f32_e32 v0, v64, v8
	v_mul_f32_e32 v4, v65, v8
	v_cvt_pk_bf16_f32 v4, v0, v4
	v_lshlrev_b32_e32 v0, 1, v212
	v_mul_f32_e32 v5, v66, v8
	v_mul_f32_e32 v6, v67, v8
	v_lshl_add_u64 v[2:3], v[2:3], 0, v[0:1]
	v_cvt_pk_bf16_f32 v5, v5, v6
	v_lshl_add_u64 v[6:7], v[2:3], 0, s[2:3]
	v_add_co_u32_e32 v2, vcc, s0, v2
	v_readlane_b32 s48, v252, 14
	s_nop 0
	v_addc_co_u32_e32 v3, vcc, 0, v3, vcc
	global_store_dwordx2 v[2:3], v[4:5], off offset:1024
	v_mul_f32_e32 v2, v68, v8
	v_mul_f32_e32 v3, v69, v8
	v_cvt_pk_bf16_f32 v2, v2, v3
	v_mul_f32_e32 v3, v70, v8
	v_mul_f32_e32 v4, v71, v8
	v_cvt_pk_bf16_f32 v3, v3, v4
	s_nop 1
	global_store_dwordx2 v[6:7], v[2:3], off offset:16
	v_mul_f32_e32 v2, v72, v8
	v_mul_f32_e32 v3, v73, v8
	v_cvt_pk_bf16_f32 v2, v2, v3
	v_mul_f32_e32 v3, v74, v8
	v_mul_f32_e32 v4, v75, v8
	v_cvt_pk_bf16_f32 v3, v3, v4
	s_nop 1
	global_store_dwordx2 v[6:7], v[2:3], off offset:32
	v_mul_f32_e32 v2, v76, v8
	v_mul_f32_e32 v3, v77, v8
	v_cvt_pk_bf16_f32 v2, v2, v3
	v_mul_f32_e32 v3, v78, v8
	v_mul_f32_e32 v4, v79, v8
	v_cvt_pk_bf16_f32 v3, v3, v4
	s_nop 1
	global_store_dwordx2 v[6:7], v[2:3], off offset:48
	v_mul_f32_e32 v2, v48, v8
	v_mul_f32_e32 v3, v49, v8
	v_cvt_pk_bf16_f32 v2, v2, v3
	v_mul_f32_e32 v3, v50, v8
	v_mul_f32_e32 v4, v51, v8
	v_cvt_pk_bf16_f32 v3, v3, v4
	s_nop 1
	global_store_dwordx2 v[6:7], v[2:3], off offset:64
	v_mul_f32_e32 v2, v52, v8
	v_mul_f32_e32 v3, v53, v8
	v_cvt_pk_bf16_f32 v2, v2, v3
	v_mul_f32_e32 v3, v54, v8
	v_mul_f32_e32 v4, v55, v8
	v_cvt_pk_bf16_f32 v3, v3, v4
	s_nop 1
	global_store_dwordx2 v[6:7], v[2:3], off offset:80
	v_mul_f32_e32 v2, v56, v8
	v_mul_f32_e32 v3, v57, v8
	v_cvt_pk_bf16_f32 v2, v2, v3
	v_mul_f32_e32 v3, v58, v8
	v_mul_f32_e32 v4, v59, v8
	v_cvt_pk_bf16_f32 v3, v3, v4
	s_nop 1
	ds_bpermute_b32 v4, v209, v15
	global_store_dwordx2 v[6:7], v[2:3], off offset:96
	v_mul_f32_e32 v2, v60, v8
	v_mul_f32_e32 v3, v61, v8
	v_cvt_pk_bf16_f32 v2, v2, v3
	v_mul_f32_e32 v3, v62, v8
	v_mul_f32_e32 v5, v63, v8
	v_cvt_pk_bf16_f32 v3, v3, v5
	s_nop 1
	global_store_dwordx2 v[6:7], v[2:3], off offset:112
	s_waitcnt lgkmcnt(0)
	v_add_f32_e32 v2, v15, v4
	v_rcp_f32_e32 v8, v2
	v_lshlrev_b64 v[2:3], 11, v[178:179]
	v_lshl_add_u64 v[2:3], s[94:95], 0, v[2:3]
	v_lshl_add_u64 v[2:3], v[2:3], 0, v[176:177]
	v_mul_f32_e32 v4, v32, v8
	v_mul_f32_e32 v5, v33, v8
	v_cvt_pk_bf16_f32 v4, v4, v5
	v_mul_f32_e32 v5, v34, v8
	v_mul_f32_e32 v6, v35, v8
	v_lshl_add_u64 v[2:3], v[2:3], 0, v[0:1]
	v_cvt_pk_bf16_f32 v5, v5, v6
	v_lshl_add_u64 v[6:7], v[2:3], 0, s[2:3]
	v_add_co_u32_e32 v2, vcc, s0, v2
	v_mul_f32_e32 v0, v36, v8
	s_nop 0
	v_addc_co_u32_e32 v3, vcc, 0, v3, vcc
	global_store_dwordx2 v[2:3], v[4:5], off offset:1024
	v_mul_f32_e32 v2, v37, v8
	v_mul_f32_e32 v3, v39, v8
	v_cvt_pk_bf16_f32 v2, v0, v2
	v_mul_f32_e32 v0, v38, v8
	v_cvt_pk_bf16_f32 v3, v0, v3
	s_nop 1
	global_store_dwordx2 v[6:7], v[2:3], off offset:16
	v_mul_f32_e32 v0, v40, v8
	v_mul_f32_e32 v2, v41, v8
	v_mul_f32_e32 v3, v43, v8
	v_cvt_pk_bf16_f32 v2, v0, v2
	v_mul_f32_e32 v0, v42, v8
	v_cvt_pk_bf16_f32 v3, v0, v3
	s_nop 1
	global_store_dwordx2 v[6:7], v[2:3], off offset:32
	v_mul_f32_e32 v0, v44, v8
	v_mul_f32_e32 v2, v45, v8
	v_mul_f32_e32 v3, v47, v8
	v_cvt_pk_bf16_f32 v2, v0, v2
	v_mul_f32_e32 v0, v46, v8
	v_cvt_pk_bf16_f32 v3, v0, v3
	s_nop 1
	global_store_dwordx2 v[6:7], v[2:3], off offset:48
	v_mul_f32_e32 v0, v16, v8
	v_mul_f32_e32 v2, v17, v8
	v_mul_f32_e32 v3, v19, v8
	v_cvt_pk_bf16_f32 v2, v0, v2
	v_mul_f32_e32 v0, v18, v8
	v_cvt_pk_bf16_f32 v3, v0, v3
	s_nop 1
	global_store_dwordx2 v[6:7], v[2:3], off offset:64
	v_mul_f32_e32 v0, v20, v8
	v_mul_f32_e32 v2, v21, v8
	v_mul_f32_e32 v3, v23, v8
	v_cvt_pk_bf16_f32 v2, v0, v2
	v_mul_f32_e32 v0, v22, v8
	v_cvt_pk_bf16_f32 v3, v0, v3
	s_nop 1
	global_store_dwordx2 v[6:7], v[2:3], off offset:80
	v_mul_f32_e32 v0, v24, v8
	v_mul_f32_e32 v2, v25, v8
	v_mul_f32_e32 v3, v27, v8
	v_cvt_pk_bf16_f32 v2, v0, v2
	v_mul_f32_e32 v0, v26, v8
	v_cvt_pk_bf16_f32 v3, v0, v3
	s_nop 1
	global_store_dwordx2 v[6:7], v[2:3], off offset:96
	v_mul_f32_e32 v0, v28, v8
	v_mul_f32_e32 v2, v29, v8
	v_mul_f32_e32 v3, v31, v8
	v_readlane_b32 s63, v252, 17
	v_readlane_b32 s65, v253, 23
	v_readlane_b32 s49, v252, 15
	v_readlane_b32 s58, v253, 19
	v_cvt_pk_bf16_f32 v2, v0, v2
	v_mul_f32_e32 v0, v30, v8
	v_cvt_pk_bf16_f32 v3, v0, v3
	s_nop 1
	global_store_dwordx2 v[6:7], v[2:3], off offset:112

.LBB0_323:
	s_nop 10
	v_max3_f32 v0, v80, s18, v81
	v_max3_f32 v0, v0, v82, v83
	v_max3_f32 v0, v0, v84, v85
	v_max3_f32 v0, v0, v86, v87
	v_max3_f32 v0, v0, v88, v89
	v_max3_f32 v0, v0, v90, v91
	v_max3_f32 v0, v0, v92, v93
	v_max3_f32 v0, v0, v94, v95
	ds_bpermute_b32 v2, v209, v0
	s_and_b64 vcc, exec, s[38:39]
	s_waitcnt lgkmcnt(0)
	v_max3_f32 v234, v231, v0, v2
	v_sub_f32_e32 v2, v81, v234
	v_exp_f32_e32 v14, v2
	v_sub_f32_e32 v2, v82, v234
	v_exp_f32_e32 v232, v2
	v_sub_f32_e32 v2, v83, v234
	v_exp_f32_e32 v236, v2
	v_sub_f32_e32 v2, v84, v234
	v_exp_f32_e32 v237, v2
	v_sub_f32_e32 v2, v85, v234
	v_exp_f32_e32 v238, v2
	v_sub_f32_e32 v2, v86, v234
	v_exp_f32_e32 v239, v2
	v_sub_f32_e32 v2, v87, v234
	v_exp_f32_e32 v240, v2
	v_sub_f32_e32 v2, v88, v234
	v_exp_f32_e32 v241, v2
	v_sub_f32_e32 v2, v89, v234
	v_exp_f32_e32 v242, v2
	v_sub_f32_e32 v2, v90, v234
	v_exp_f32_e32 v243, v2
	v_sub_f32_e32 v2, v91, v234
	v_exp_f32_e32 v244, v2
	v_sub_f32_e32 v2, v92, v234
	v_exp_f32_e32 v245, v2
	v_sub_f32_e32 v2, v93, v234
	v_exp_f32_e32 v246, v2
	v_sub_f32_e32 v2, v94, v234
	v_sub_f32_e32 v0, v80, v234
	v_exp_f32_e32 v247, v2
	v_sub_f32_e32 v2, v95, v234
	v_mfma_f32_32x32x16_bf16 v[80:95], v[168:171], v[112:115], 0
	v_exp_f32_e32 v0, v0
	v_exp_f32_e32 v248, v2
	v_cvt_pk_bf16_f32 v6, v0, v14
	v_cvt_pk_bf16_f32 v7, v232, v236
	v_cvt_pk_bf16_f32 v8, v237, v238
	v_cvt_pk_bf16_f32 v9, v239, v240
	v_cvt_pk_bf16_f32 v2, v241, v242
	v_mfma_f32_32x32x16_bf16 v[80:95], v[164:167], v[116:119], v[80:95]
	v_cvt_pk_bf16_f32 v3, v243, v244
	v_cvt_pk_bf16_f32 v4, v245, v246
	v_cvt_pk_bf16_f32 v5, v247, v248
	v_mfma_f32_32x32x16_bf16 v[80:95], v[10:13], v[120:123], v[80:95]
	v_mfma_f32_32x32x16_bf16 v[80:95], v[160:163], v[124:127], v[80:95]
	s_cbranch_vccnz .LBB0_326
	s_cmp_lt_i32 s3, s62
	s_cselect_b64 s[0:1], -1, 0
	s_cmp_gt_i32 s3, s55
	s_cselect_b64 s[26:27], -1, 0
	s_or_b64 s[0:1], s[0:1], s[26:27]
	s_andn2_b64 vcc, exec, s[0:1]
	s_cbranch_vccnz .LBB0_326
	s_sub_i32 s0, s33, s63
	v_add_u32_e32 v10, s0, v214
	v_cmp_lt_u32_e32 vcc, s66, v10
	v_add_u32_e32 v10, s0, v215
	s_nop 0
	v_cndmask_b32_e32 v80, v200, v80, vcc
	v_cmp_lt_u32_e32 vcc, s66, v10
	v_add_u32_e32 v10, s0, v216
	s_nop 0
	v_cndmask_b32_e32 v81, v200, v81, vcc
	v_cmp_lt_u32_e32 vcc, s66, v10
	v_add_u32_e32 v10, s0, v217
	s_nop 0
	v_cndmask_b32_e32 v82, v200, v82, vcc
	v_cmp_lt_u32_e32 vcc, s66, v10
	v_add_u32_e32 v10, s0, v218
	s_nop 0
	v_cndmask_b32_e32 v83, v200, v83, vcc
	v_cmp_lt_u32_e32 vcc, s66, v10
	v_add_u32_e32 v10, s0, v219
	s_nop 0
	v_cndmask_b32_e32 v84, v200, v84, vcc
	v_cmp_lt_u32_e32 vcc, s66, v10
	v_add_u32_e32 v10, s0, v220
	s_nop 0
	v_cndmask_b32_e32 v85, v200, v85, vcc
	v_cmp_lt_u32_e32 vcc, s66, v10
	v_add_u32_e32 v10, s0, v221
	s_nop 0
	v_cndmask_b32_e32 v86, v200, v86, vcc
	v_cmp_lt_u32_e32 vcc, s66, v10
	v_add_u32_e32 v10, s0, v222
	s_nop 0
	v_cndmask_b32_e32 v87, v200, v87, vcc
	v_cmp_lt_u32_e32 vcc, s66, v10
	v_add_u32_e32 v10, s0, v223
	s_nop 0
	v_cndmask_b32_e32 v88, v200, v88, vcc
	v_cmp_lt_u32_e32 vcc, s66, v10
	v_add_u32_e32 v10, s0, v224
	s_nop 0
	v_cndmask_b32_e32 v89, v200, v89, vcc
	v_cmp_lt_u32_e32 vcc, s66, v10
	v_add_u32_e32 v10, s0, v225
	s_nop 0
	v_cndmask_b32_e32 v90, v200, v90, vcc
	v_cmp_lt_u32_e32 vcc, s66, v10
	v_add_u32_e32 v10, s0, v226
	s_nop 0
	v_cndmask_b32_e32 v91, v200, v91, vcc
	v_cmp_lt_u32_e32 vcc, s66, v10
	v_add_u32_e32 v10, s0, v227
	s_nop 0
	v_cndmask_b32_e32 v92, v200, v92, vcc
	v_cmp_lt_u32_e32 vcc, s66, v10
	v_add_u32_e32 v10, s0, v228
	s_nop 0
	v_cndmask_b32_e32 v93, v200, v93, vcc
	v_cmp_lt_u32_e32 vcc, s66, v10
	v_add_u32_e32 v10, s0, v229
	s_nop 0
	v_cndmask_b32_e32 v94, v200, v94, vcc
	v_cmp_lt_u32_e32 vcc, s66, v10
	s_nop 1
	v_cndmask_b32_e32 v95, v200, v95, vcc
.LBB0_326:
	v_add_f32_e32 v0, 0, v0
	v_add_f32_e32 v0, v14, v0
	v_add_f32_e32 v0, v232, v0
	v_add_f32_e32 v0, v236, v0
	v_add_f32_e32 v0, v237, v0
	v_add_f32_e32 v0, v238, v0
	v_add_f32_e32 v0, v239, v0
	v_add_f32_e32 v0, v240, v0
	v_add_f32_e32 v0, v241, v0
	v_add_f32_e32 v0, v242, v0
	v_add_f32_e32 v0, v243, v0
	v_add_f32_e32 v0, v244, v0
	v_add_f32_e32 v0, v245, v0
	v_add_f32_e32 v0, v246, v0
	v_sub_f32_e32 v10, v231, v234
	v_add_f32_e32 v0, v247, v0
	v_add_f32_e32 v232, v248, v0
	v_exp_f32_e32 v0, v10
	v_add_u32_e32 v231, 0x1000, v230
	s_add_i32 s0, s64, -7
	s_cmp_ge_i32 s0, s56
	v_fmac_f32_e32 v232, v233, v0
	v_mul_f32_e32 v78, v0, v78
	v_mul_f32_e32 v79, v0, v79
	v_mul_f32_e32 v76, v0, v76
	v_mul_f32_e32 v77, v0, v77
	v_mul_f32_e32 v74, v0, v74
	v_mul_f32_e32 v75, v0, v75
	v_mul_f32_e32 v72, v0, v72
	v_mul_f32_e32 v73, v0, v73
	v_mul_f32_e32 v70, v0, v70
	v_mul_f32_e32 v71, v0, v71
	v_mul_f32_e32 v68, v0, v68
	v_mul_f32_e32 v69, v0, v69
	v_mul_f32_e32 v66, v0, v66
	v_mul_f32_e32 v67, v0, v67
	v_mul_f32_e32 v64, v0, v64
	v_mul_f32_e32 v65, v0, v65
	v_mul_f32_e32 v62, v0, v62
	v_mul_f32_e32 v63, v0, v63
	v_mul_f32_e32 v60, v0, v60
	v_mul_f32_e32 v61, v0, v61
	v_mul_f32_e32 v58, v0, v58
	v_mul_f32_e32 v59, v0, v59
	v_mul_f32_e32 v56, v0, v56
	v_mul_f32_e32 v57, v0, v57
	v_mul_f32_e32 v54, v0, v54
	v_mul_f32_e32 v55, v0, v55
	v_mul_f32_e32 v52, v0, v52
	v_mul_f32_e32 v53, v0, v53
	v_mul_f32_e32 v50, v0, v50
	v_mul_f32_e32 v51, v0, v51
	v_mul_f32_e32 v48, v0, v48
	v_mul_f32_e32 v49, v0, v49
	v_max3_f32 v0, v80, s18, v81
	v_max3_f32 v0, v0, v82, v83
	v_max3_f32 v0, v0, v84, v85
	v_max3_f32 v0, v0, v86, v87
	v_max3_f32 v0, v0, v88, v89
	v_max3_f32 v0, v0, v90, v91
	v_max3_f32 v0, v0, v92, v93
	v_max3_f32 v0, v0, v94, v95
	ds_bpermute_b32 v10, v209, v0
	s_waitcnt lgkmcnt(0)
	v_max3_f32 v14, v235, v0, v10
	v_sub_f32_e32 v0, v80, v14
	v_exp_f32_e32 v11, v0
	v_sub_f32_e32 v12, v81, v14
	v_exp_f32_e32 v12, v12
	v_sub_f32_e32 v13, v82, v14
	v_exp_f32_e32 v13, v13
	v_sub_f32_e32 v80, v83, v14
	v_exp_f32_e32 v81, v80
	v_sub_f32_e32 v80, v84, v14
	v_add_f32_e32 v0, 0, v11
	v_exp_f32_e32 v82, v80
	v_sub_f32_e32 v80, v85, v14
	v_add_f32_e32 v0, v12, v0
	v_exp_f32_e32 v83, v80
	v_sub_f32_e32 v80, v86, v14
	v_add_f32_e32 v0, v13, v0
	v_exp_f32_e32 v84, v80
	v_sub_f32_e32 v80, v87, v14
	v_add_f32_e32 v0, v81, v0
	v_exp_f32_e32 v85, v80
	v_sub_f32_e32 v80, v88, v14
	v_add_f32_e32 v0, v82, v0
	v_exp_f32_e32 v86, v80
	v_sub_f32_e32 v80, v89, v14
	v_add_f32_e32 v0, v83, v0
	v_exp_f32_e32 v87, v80
	v_sub_f32_e32 v80, v90, v14
	v_add_f32_e32 v0, v84, v0
	v_exp_f32_e32 v88, v80
	v_sub_f32_e32 v80, v91, v14
	v_add_f32_e32 v0, v85, v0
	v_exp_f32_e32 v89, v80
	v_sub_f32_e32 v80, v92, v14
	v_add_f32_e32 v0, v86, v0
	v_exp_f32_e32 v90, v80
	v_sub_f32_e32 v80, v93, v14
	v_add_f32_e32 v0, v87, v0
	v_exp_f32_e32 v91, v80
	v_sub_f32_e32 v80, v94, v14
	v_add_f32_e32 v0, v88, v0
	v_exp_f32_e32 v92, v80
	v_sub_f32_e32 v80, v95, v14
	v_sub_f32_e32 v10, v235, v14
	v_add_f32_e32 v0, v89, v0
	v_exp_f32_e32 v93, v80
	v_add_f32_e32 v0, v90, v0
	v_exp_f32_e32 v10, v10
	v_add_f32_e32 v0, v91, v0
	v_add_f32_e32 v0, v92, v0
	v_add_f32_e32 v0, v93, v0
	v_fmac_f32_e32 v0, v15, v10
	v_mul_f32_e32 v46, v10, v46
	v_mul_f32_e32 v47, v10, v47
	v_mul_f32_e32 v44, v10, v44
	v_mul_f32_e32 v45, v10, v45
	v_mul_f32_e32 v42, v10, v42
	v_mul_f32_e32 v43, v10, v43
	v_mul_f32_e32 v40, v10, v40
	v_mul_f32_e32 v41, v10, v41
	v_mul_f32_e32 v38, v10, v38
	v_mul_f32_e32 v39, v10, v39
	v_mul_f32_e32 v36, v10, v36
	v_mul_f32_e32 v37, v10, v37
	v_mul_f32_e32 v34, v10, v34
	v_mul_f32_e32 v35, v10, v35
	v_mul_f32_e32 v32, v10, v32
	v_mul_f32_e32 v33, v10, v33
	v_mul_f32_e32 v30, v10, v30
	v_mul_f32_e32 v31, v10, v31
	v_mul_f32_e32 v28, v10, v28
	v_mul_f32_e32 v29, v10, v29
	v_mul_f32_e32 v26, v10, v26
	v_mul_f32_e32 v27, v10, v27
	v_mul_f32_e32 v24, v10, v24
	v_mul_f32_e32 v25, v10, v25
	v_mul_f32_e32 v22, v10, v22
	v_mul_f32_e32 v23, v10, v23
	v_mul_f32_e32 v20, v10, v20
	v_mul_f32_e32 v21, v10, v21
	v_mul_f32_e32 v18, v10, v18
	v_mul_f32_e32 v19, v10, v19
	v_mul_f32_e32 v16, v10, v16
	v_mul_f32_e32 v17, v10, v17
	v_cvt_pk_bf16_f32 v80, v11, v12
	v_cvt_pk_bf16_f32 v82, v82, v83
	v_cvt_pk_bf16_f32 v83, v84, v85
	v_cvt_pk_bf16_f32 v10, v86, v87
	v_cvt_pk_bf16_f32 v11, v88, v89
	v_cvt_pk_bf16_f32 v12, v90, v91
	ds_read2_b64 v[84:87], v231 offset0:64 offset1:66
	ds_read2_b64 v[88:91], v231 offset0:68 offset1:70
	v_add_u32_e32 v15, 0x1800, v230
	v_cvt_pk_bf16_f32 v81, v13, v81
	s_waitcnt lgkmcnt(1)
	v_mfma_f32_32x32x16_bf16 v[64:79], v[84:87], v[6:9], v[64:79]
	v_cvt_pk_bf16_f32 v13, v92, v93
	v_mfma_f32_32x32x16_bf16 v[32:47], v[84:87], v[80:83], v[32:47]
	ds_read2_b64 v[84:87], v15 offset0:128 offset1:130
	s_waitcnt lgkmcnt(0)
	v_mfma_f32_32x32x16_bf16 v[48:63], v[84:87], v[6:9], v[48:63]
	ds_read2_b64 v[6:9], v15 offset0:132 offset1:134
	s_waitcnt lgkmcnt(0)
	s_barrier
	v_mfma_f32_32x32x16_bf16 v[16:31], v[84:87], v[80:83], v[16:31]
	v_mfma_f32_32x32x16_bf16 v[64:79], v[88:91], v[2:5], v[64:79]
	v_mfma_f32_32x32x16_bf16 v[32:47], v[88:91], v[10:13], v[32:47]
	v_mfma_f32_32x32x16_bf16 v[48:63], v[6:9], v[2:5], v[48:63]
	v_mfma_f32_32x32x16_bf16 v[16:31], v[6:9], v[10:13], v[16:31]
	s_cbranch_scc1 .LBB0_330
	s_cmp_lt_i32 s0, s53
	s_cselect_b64 s[34:35], -1, 0
	s_mov_b64 s[40:41], -1
	s_and_b64 vcc, exec, s[34:35]
	s_cbranch_vccz .LBB0_333
	s_andn2_b64 vcc, exec, s[40:41]
	s_cbranch_vccz .LBB0_334

.LBB0_344:
	s_nop 10
	v_max3_f32 v2, v80, s18, v81
	v_max3_f32 v2, v2, v82, v83
	v_max3_f32 v2, v2, v84, v85
	v_max3_f32 v2, v2, v86, v87
	v_max3_f32 v2, v2, v88, v89
	v_max3_f32 v2, v2, v90, v91
	v_max3_f32 v2, v2, v92, v93
	v_max3_f32 v2, v2, v94, v95
	ds_bpermute_b32 v3, v209, v2
	s_and_b64 vcc, exec, s[40:41]
	s_waitcnt lgkmcnt(0)
	v_max3_f32 v233, v234, v2, v3
	v_sub_f32_e32 v2, v80, v233
	v_exp_f32_e32 v235, v2
	v_sub_f32_e32 v2, v81, v233
	v_exp_f32_e32 v236, v2
	v_sub_f32_e32 v2, v82, v233
	v_exp_f32_e32 v237, v2
	v_sub_f32_e32 v2, v83, v233
	v_exp_f32_e32 v238, v2
	v_sub_f32_e32 v2, v84, v233
	v_exp_f32_e32 v239, v2
	v_sub_f32_e32 v2, v85, v233
	v_exp_f32_e32 v240, v2
	v_sub_f32_e32 v2, v86, v233
	v_exp_f32_e32 v241, v2
	v_sub_f32_e32 v2, v87, v233
	v_exp_f32_e32 v242, v2
	v_sub_f32_e32 v2, v88, v233
	v_exp_f32_e32 v243, v2
	v_sub_f32_e32 v2, v89, v233
	v_exp_f32_e32 v244, v2
	v_sub_f32_e32 v2, v90, v233
	v_exp_f32_e32 v245, v2
	v_sub_f32_e32 v2, v91, v233
	v_exp_f32_e32 v246, v2
	v_sub_f32_e32 v2, v92, v233
	v_exp_f32_e32 v247, v2
	v_sub_f32_e32 v2, v93, v233
	v_exp_f32_e32 v248, v2
	v_sub_f32_e32 v2, v94, v233
	v_exp_f32_e32 v249, v2
	v_sub_f32_e32 v2, v95, v233
	v_mfma_f32_32x32x16_bf16 v[80:95], v[168:171], v[112:115], 0
	v_exp_f32_e32 v250, v2
	v_cvt_pk_bf16_f32 v6, v235, v236
	v_cvt_pk_bf16_f32 v7, v237, v238
	v_cvt_pk_bf16_f32 v8, v239, v240
	v_cvt_pk_bf16_f32 v9, v241, v242
	v_cvt_pk_bf16_f32 v2, v243, v244
	v_cvt_pk_bf16_f32 v3, v245, v246
	v_mfma_f32_32x32x16_bf16 v[80:95], v[164:167], v[116:119], v[80:95]
	v_cvt_pk_bf16_f32 v4, v247, v248
	v_cvt_pk_bf16_f32 v5, v249, v250
	v_mfma_f32_32x32x16_bf16 v[80:95], v[10:13], v[120:123], v[80:95]
	v_mfma_f32_32x32x16_bf16 v[80:95], v[160:163], v[124:127], v[80:95]
	s_cbranch_vccnz .LBB0_347
	s_cmp_lt_i32 s3, s62
	s_cselect_b64 s[0:1], -1, 0
	s_cmp_gt_i32 s3, s55
	s_cselect_b64 s[26:27], -1, 0
	s_or_b64 s[0:1], s[0:1], s[26:27]
	s_andn2_b64 vcc, exec, s[0:1]
	s_cbranch_vccnz .LBB0_347
	s_sub_i32 s0, s33, s63
	v_add_u32_e32 v10, s0, v214
	v_cmp_lt_u32_e32 vcc, s66, v10
	v_add_u32_e32 v10, s0, v215
	s_nop 0
	v_cndmask_b32_e32 v80, v200, v80, vcc
	v_cmp_lt_u32_e32 vcc, s66, v10
	v_add_u32_e32 v10, s0, v216
	s_nop 0
	v_cndmask_b32_e32 v81, v200, v81, vcc
	v_cmp_lt_u32_e32 vcc, s66, v10
	v_add_u32_e32 v10, s0, v217
	s_nop 0
	v_cndmask_b32_e32 v82, v200, v82, vcc
	v_cmp_lt_u32_e32 vcc, s66, v10
	v_add_u32_e32 v10, s0, v218
	s_nop 0
	v_cndmask_b32_e32 v83, v200, v83, vcc
	v_cmp_lt_u32_e32 vcc, s66, v10
	v_add_u32_e32 v10, s0, v219
	s_nop 0
	v_cndmask_b32_e32 v84, v200, v84, vcc
	v_cmp_lt_u32_e32 vcc, s66, v10
	v_add_u32_e32 v10, s0, v220
	s_nop 0
	v_cndmask_b32_e32 v85, v200, v85, vcc
	v_cmp_lt_u32_e32 vcc, s66, v10
	v_add_u32_e32 v10, s0, v221
	s_nop 0
	v_cndmask_b32_e32 v86, v200, v86, vcc
	v_cmp_lt_u32_e32 vcc, s66, v10
	v_add_u32_e32 v10, s0, v222
	s_nop 0
	v_cndmask_b32_e32 v87, v200, v87, vcc
	v_cmp_lt_u32_e32 vcc, s66, v10
	v_add_u32_e32 v10, s0, v223
	s_nop 0
	v_cndmask_b32_e32 v88, v200, v88, vcc
	v_cmp_lt_u32_e32 vcc, s66, v10
	v_add_u32_e32 v10, s0, v224
	s_nop 0
	v_cndmask_b32_e32 v89, v200, v89, vcc
	v_cmp_lt_u32_e32 vcc, s66, v10
	v_add_u32_e32 v10, s0, v225
	s_nop 0
	v_cndmask_b32_e32 v90, v200, v90, vcc
	v_cmp_lt_u32_e32 vcc, s66, v10
	v_add_u32_e32 v10, s0, v226
	s_nop 0
	v_cndmask_b32_e32 v91, v200, v91, vcc
	v_cmp_lt_u32_e32 vcc, s66, v10
	v_add_u32_e32 v10, s0, v227
	s_nop 0
	v_cndmask_b32_e32 v92, v200, v92, vcc
	v_cmp_lt_u32_e32 vcc, s66, v10
	v_add_u32_e32 v10, s0, v228
	s_nop 0
	v_cndmask_b32_e32 v93, v200, v93, vcc
	v_cmp_lt_u32_e32 vcc, s66, v10
	v_add_u32_e32 v10, s0, v229
	s_nop 0
	v_cndmask_b32_e32 v94, v200, v94, vcc
	v_cmp_lt_u32_e32 vcc, s66, v10
	s_nop 1
	v_cndmask_b32_e32 v95, v200, v95, vcc
.LBB0_347:
	v_add_f32_e32 v11, 0, v235
	v_add_f32_e32 v11, v236, v11
	v_add_f32_e32 v11, v237, v11
	v_add_f32_e32 v11, v238, v11
	v_add_f32_e32 v11, v239, v11
	v_add_f32_e32 v11, v240, v11
	v_add_f32_e32 v11, v241, v11
	v_add_f32_e32 v11, v242, v11
	v_add_f32_e32 v11, v243, v11
	v_add_f32_e32 v11, v244, v11
	v_add_f32_e32 v11, v245, v11
	v_sub_f32_e32 v10, v234, v233
	v_add_f32_e32 v11, v246, v11
	v_add_f32_e32 v11, v247, v11
	v_exp_f32_e32 v10, v10
	v_add_f32_e32 v11, v248, v11
	v_add_f32_e32 v11, v249, v11
	v_add_f32_e32 v160, v250, v11
	v_fmac_f32_e32 v160, v232, v10
	v_mul_f32_e32 v78, v10, v78
	v_mul_f32_e32 v79, v10, v79
	v_mul_f32_e32 v76, v10, v76
	v_mul_f32_e32 v77, v10, v77
	v_mul_f32_e32 v74, v10, v74
	v_mul_f32_e32 v75, v10, v75
	v_mul_f32_e32 v72, v10, v72
	v_mul_f32_e32 v73, v10, v73
	v_mul_f32_e32 v70, v10, v70
	v_mul_f32_e32 v71, v10, v71
	v_mul_f32_e32 v68, v10, v68
	v_mul_f32_e32 v69, v10, v69
	v_mul_f32_e32 v66, v10, v66
	v_mul_f32_e32 v67, v10, v67
	v_mul_f32_e32 v64, v10, v64
	v_mul_f32_e32 v65, v10, v65
	v_mul_f32_e32 v62, v10, v62
	v_mul_f32_e32 v63, v10, v63
	v_mul_f32_e32 v60, v10, v60
	v_mul_f32_e32 v61, v10, v61
	v_mul_f32_e32 v58, v10, v58
	v_mul_f32_e32 v59, v10, v59
	v_mul_f32_e32 v56, v10, v56
	v_mul_f32_e32 v57, v10, v57
	v_mul_f32_e32 v54, v10, v54
	v_mul_f32_e32 v55, v10, v55
	v_mul_f32_e32 v52, v10, v52
	v_mul_f32_e32 v53, v10, v53
	v_mul_f32_e32 v50, v10, v50
	v_mul_f32_e32 v51, v10, v51
	v_mul_f32_e32 v48, v10, v48
	v_mul_f32_e32 v49, v10, v49
	v_max3_f32 v10, v80, s18, v81
	v_max3_f32 v10, v10, v82, v83
	v_max3_f32 v10, v10, v84, v85
	v_max3_f32 v10, v10, v86, v87
	v_max3_f32 v10, v10, v88, v89
	v_max3_f32 v10, v10, v90, v91
	v_max3_f32 v10, v10, v92, v93
	v_max3_f32 v10, v10, v94, v95
	ds_bpermute_b32 v11, v209, v10
	v_mov_b32_e32 v232, v160
	s_waitcnt lgkmcnt(0)
	v_max3_f32 v161, v14, v10, v11
	v_sub_f32_e32 v11, v80, v161
	v_exp_f32_e32 v11, v11
	v_sub_f32_e32 v13, v81, v161
	v_sub_f32_e32 v10, v14, v161
	v_exp_f32_e32 v13, v13
	v_sub_f32_e32 v14, v82, v161
	v_exp_f32_e32 v14, v14
	v_sub_f32_e32 v80, v83, v161
	v_exp_f32_e32 v81, v80
	v_sub_f32_e32 v80, v84, v161
	v_add_f32_e32 v12, 0, v11
	v_exp_f32_e32 v82, v80
	v_sub_f32_e32 v80, v85, v161
	v_add_f32_e32 v12, v13, v12
	v_exp_f32_e32 v83, v80
	v_sub_f32_e32 v80, v86, v161
	v_add_f32_e32 v12, v14, v12
	v_exp_f32_e32 v85, v80
	v_sub_f32_e32 v80, v87, v161
	v_add_f32_e32 v12, v81, v12
	v_exp_f32_e32 v86, v80
	v_sub_f32_e32 v80, v88, v161
	v_add_f32_e32 v12, v82, v12
	v_exp_f32_e32 v87, v80
	v_sub_f32_e32 v80, v89, v161
	v_add_f32_e32 v12, v83, v12
	v_exp_f32_e32 v88, v80
	v_sub_f32_e32 v80, v90, v161
	v_add_f32_e32 v12, v85, v12
	v_exp_f32_e32 v89, v80
	v_sub_f32_e32 v80, v91, v161
	v_add_f32_e32 v12, v86, v12
	v_exp_f32_e32 v90, v80
	v_sub_f32_e32 v80, v92, v161
	v_add_f32_e32 v12, v87, v12
	v_exp_f32_e32 v91, v80
	v_sub_f32_e32 v80, v93, v161
	v_add_f32_e32 v12, v88, v12
	v_exp_f32_e32 v92, v80
	v_sub_f32_e32 v80, v94, v161
	v_add_f32_e32 v12, v89, v12
	v_exp_f32_e32 v93, v80
	v_sub_f32_e32 v80, v95, v161
	v_add_f32_e32 v12, v90, v12
	v_exp_f32_e32 v94, v80
	v_add_f32_e32 v12, v91, v12
	v_exp_f32_e32 v10, v10
	v_add_f32_e32 v12, v92, v12
	v_add_f32_e32 v12, v93, v12
	v_add_f32_e32 v84, v94, v12
	v_fmac_f32_e32 v84, v0, v10
	v_add_u32_e32 v0, 0x3800, v230
	v_mul_f32_e32 v46, v10, v46
	v_mul_f32_e32 v47, v10, v47
	v_mul_f32_e32 v44, v10, v44
	v_mul_f32_e32 v45, v10, v45
	v_mul_f32_e32 v42, v10, v42
	v_mul_f32_e32 v43, v10, v43
	v_mul_f32_e32 v40, v10, v40
	v_mul_f32_e32 v41, v10, v41
	v_mul_f32_e32 v38, v10, v38
	v_mul_f32_e32 v39, v10, v39
	v_mul_f32_e32 v36, v10, v36
	v_mul_f32_e32 v37, v10, v37
	v_mul_f32_e32 v34, v10, v34
	v_mul_f32_e32 v35, v10, v35
	v_mul_f32_e32 v32, v10, v32
	v_mul_f32_e32 v33, v10, v33
	v_mul_f32_e32 v30, v10, v30
	v_mul_f32_e32 v31, v10, v31
	v_mul_f32_e32 v28, v10, v28
	v_mul_f32_e32 v29, v10, v29
	v_mul_f32_e32 v26, v10, v26
	v_mul_f32_e32 v27, v10, v27
	v_mul_f32_e32 v24, v10, v24
	v_mul_f32_e32 v25, v10, v25
	v_mul_f32_e32 v22, v10, v22
	v_mul_f32_e32 v23, v10, v23
	v_mul_f32_e32 v20, v10, v20
	v_mul_f32_e32 v21, v10, v21
	v_mul_f32_e32 v18, v10, v18
	v_mul_f32_e32 v19, v10, v19
	v_mul_f32_e32 v16, v10, v16
	v_mul_f32_e32 v17, v10, v17
	v_cvt_pk_bf16_f32 v80, v11, v13
	v_cvt_pk_bf16_f32 v82, v82, v83
	v_cvt_pk_bf16_f32 v83, v85, v86
	v_cvt_pk_bf16_f32 v10, v87, v88
	v_cvt_pk_bf16_f32 v11, v89, v90
	v_cvt_pk_bf16_f32 v12, v91, v92
	v_cvt_pk_bf16_f32 v13, v93, v94
	ds_read2_b64 v[86:89], v0 offset1:2
	ds_read2_b64 v[90:93], v0 offset0:4 offset1:6
	v_add_u32_e32 v0, 0x4000, v230
	v_cvt_pk_bf16_f32 v81, v14, v81
	s_waitcnt lgkmcnt(1)
	v_mfma_f32_32x32x16_bf16 v[64:79], v[86:89], v[6:9], v[64:79]
	v_mov_b32_e32 v14, v161
	v_mfma_f32_32x32x16_bf16 v[32:47], v[86:89], v[80:83], v[32:47]
	ds_read2_b64 v[86:89], v0 offset0:64 offset1:66
	s_waitcnt lgkmcnt(0)
	v_mfma_f32_32x32x16_bf16 v[48:63], v[86:89], v[6:9], v[48:63]
	ds_read2_b64 v[6:9], v0 offset0:68 offset1:70
	v_mov_b32_e32 v0, v84
	s_waitcnt lgkmcnt(0)
	s_barrier
	v_mfma_f32_32x32x16_bf16 v[16:31], v[86:89], v[80:83], v[16:31]
	v_mfma_f32_32x32x16_bf16 v[64:79], v[90:93], v[2:5], v[64:79]
	v_mfma_f32_32x32x16_bf16 v[32:47], v[90:93], v[10:13], v[32:47]
	v_mfma_f32_32x32x16_bf16 v[48:63], v[6:9], v[2:5], v[48:63]
	v_mfma_f32_32x32x16_bf16 v[16:31], v[6:9], v[10:13], v[16:31]
	s_add_i32 s0, s64, -6
	s_cmp_ge_i32 s0, s56
	s_cbranch_scc1 .LBB0_331

.LBB0_362:
	s_nop 10
	v_max3_f32 v2, v80, s18, v81
	v_max3_f32 v2, v2, v82, v83
	v_max3_f32 v2, v2, v84, v85
	v_max3_f32 v2, v2, v86, v87
	v_max3_f32 v2, v2, v88, v89
	v_max3_f32 v2, v2, v90, v91
	v_max3_f32 v2, v2, v92, v93
	v_max3_f32 v2, v2, v94, v95
	ds_bpermute_b32 v3, v209, v2
	s_and_b64 vcc, exec, s[40:41]
	s_waitcnt lgkmcnt(0)
	v_max3_f32 v234, v233, v2, v3
	v_sub_f32_e32 v2, v80, v234
	v_exp_f32_e32 v235, v2
	v_sub_f32_e32 v2, v81, v234
	v_exp_f32_e32 v236, v2
	v_sub_f32_e32 v2, v82, v234
	v_exp_f32_e32 v237, v2
	v_sub_f32_e32 v2, v83, v234
	v_exp_f32_e32 v238, v2
	v_sub_f32_e32 v2, v84, v234
	v_exp_f32_e32 v239, v2
	v_sub_f32_e32 v2, v85, v234
	v_exp_f32_e32 v240, v2
	v_sub_f32_e32 v2, v86, v234
	v_exp_f32_e32 v241, v2
	v_sub_f32_e32 v2, v87, v234
	v_exp_f32_e32 v242, v2
	v_sub_f32_e32 v2, v88, v234
	v_exp_f32_e32 v243, v2
	v_sub_f32_e32 v2, v89, v234
	v_exp_f32_e32 v244, v2
	v_sub_f32_e32 v2, v90, v234
	v_exp_f32_e32 v245, v2
	v_sub_f32_e32 v2, v91, v234
	v_exp_f32_e32 v246, v2
	v_sub_f32_e32 v2, v92, v234
	v_exp_f32_e32 v247, v2
	v_sub_f32_e32 v2, v93, v234
	v_exp_f32_e32 v248, v2
	v_sub_f32_e32 v2, v94, v234
	v_exp_f32_e32 v249, v2
	v_sub_f32_e32 v2, v95, v234
	v_mfma_f32_32x32x16_bf16 v[80:95], v[168:171], v[112:115], 0
	v_exp_f32_e32 v250, v2
	v_cvt_pk_bf16_f32 v6, v235, v236
	v_cvt_pk_bf16_f32 v7, v237, v238
	v_cvt_pk_bf16_f32 v8, v239, v240
	v_cvt_pk_bf16_f32 v9, v241, v242
	v_cvt_pk_bf16_f32 v2, v243, v244
	v_cvt_pk_bf16_f32 v3, v245, v246
	v_mfma_f32_32x32x16_bf16 v[80:95], v[164:167], v[116:119], v[80:95]
	v_cvt_pk_bf16_f32 v4, v247, v248
	v_cvt_pk_bf16_f32 v5, v249, v250
	v_mfma_f32_32x32x16_bf16 v[80:95], v[10:13], v[120:123], v[80:95]
	v_mfma_f32_32x32x16_bf16 v[80:95], v[160:163], v[124:127], v[80:95]
	s_cbranch_vccnz .LBB0_365
	s_cmp_lt_i32 s3, s62
	s_cselect_b64 s[0:1], -1, 0
	s_cmp_gt_i32 s3, s55
	s_cselect_b64 s[26:27], -1, 0
	s_or_b64 s[0:1], s[0:1], s[26:27]
	s_andn2_b64 vcc, exec, s[0:1]
	s_cbranch_vccnz .LBB0_365
	s_sub_i32 s0, s33, s63
	v_add_u32_e32 v10, s0, v214
	v_cmp_lt_u32_e32 vcc, s66, v10
	v_add_u32_e32 v10, s0, v215
	s_nop 0
	v_cndmask_b32_e32 v80, v200, v80, vcc
	v_cmp_lt_u32_e32 vcc, s66, v10
	v_add_u32_e32 v10, s0, v216
	s_nop 0
	v_cndmask_b32_e32 v81, v200, v81, vcc
	v_cmp_lt_u32_e32 vcc, s66, v10
	v_add_u32_e32 v10, s0, v217
	s_nop 0
	v_cndmask_b32_e32 v82, v200, v82, vcc
	v_cmp_lt_u32_e32 vcc, s66, v10
	v_add_u32_e32 v10, s0, v218
	s_nop 0
	v_cndmask_b32_e32 v83, v200, v83, vcc
	v_cmp_lt_u32_e32 vcc, s66, v10
	v_add_u32_e32 v10, s0, v219
	s_nop 0
	v_cndmask_b32_e32 v84, v200, v84, vcc
	v_cmp_lt_u32_e32 vcc, s66, v10
	v_add_u32_e32 v10, s0, v220
	s_nop 0
	v_cndmask_b32_e32 v85, v200, v85, vcc
	v_cmp_lt_u32_e32 vcc, s66, v10
	v_add_u32_e32 v10, s0, v221
	s_nop 0
	v_cndmask_b32_e32 v86, v200, v86, vcc
	v_cmp_lt_u32_e32 vcc, s66, v10
	v_add_u32_e32 v10, s0, v222
	s_nop 0
	v_cndmask_b32_e32 v87, v200, v87, vcc
	v_cmp_lt_u32_e32 vcc, s66, v10
	v_add_u32_e32 v10, s0, v223
	s_nop 0
	v_cndmask_b32_e32 v88, v200, v88, vcc
	v_cmp_lt_u32_e32 vcc, s66, v10
	v_add_u32_e32 v10, s0, v224
	s_nop 0
	v_cndmask_b32_e32 v89, v200, v89, vcc
	v_cmp_lt_u32_e32 vcc, s66, v10
	v_add_u32_e32 v10, s0, v225
	s_nop 0
	v_cndmask_b32_e32 v90, v200, v90, vcc
	v_cmp_lt_u32_e32 vcc, s66, v10
	v_add_u32_e32 v10, s0, v226
	s_nop 0
	v_cndmask_b32_e32 v91, v200, v91, vcc
	v_cmp_lt_u32_e32 vcc, s66, v10
	v_add_u32_e32 v10, s0, v227
	s_nop 0
	v_cndmask_b32_e32 v92, v200, v92, vcc
	v_cmp_lt_u32_e32 vcc, s66, v10
	v_add_u32_e32 v10, s0, v228
	s_nop 0
	v_cndmask_b32_e32 v93, v200, v93, vcc
	v_cmp_lt_u32_e32 vcc, s66, v10
	v_add_u32_e32 v10, s0, v229
	s_nop 0
	v_cndmask_b32_e32 v94, v200, v94, vcc
	v_cmp_lt_u32_e32 vcc, s66, v10
	s_nop 1
	v_cndmask_b32_e32 v95, v200, v95, vcc
.LBB0_365:
	v_add_f32_e32 v11, 0, v235
	v_add_f32_e32 v11, v236, v11
	v_add_f32_e32 v11, v237, v11
	v_add_f32_e32 v11, v238, v11
	v_add_f32_e32 v11, v239, v11
	v_add_f32_e32 v11, v240, v11
	v_add_f32_e32 v11, v241, v11
	v_add_f32_e32 v11, v242, v11
	v_add_f32_e32 v11, v243, v11
	v_add_f32_e32 v11, v244, v11
	v_add_f32_e32 v11, v245, v11
	v_sub_f32_e32 v10, v233, v234
	v_add_f32_e32 v11, v246, v11
	v_add_f32_e32 v11, v247, v11
	v_exp_f32_e32 v10, v10
	v_add_f32_e32 v11, v248, v11
	v_add_f32_e32 v11, v249, v11
	v_add_f32_e32 v160, v250, v11
	v_fmac_f32_e32 v160, v232, v10
	v_mul_f32_e32 v78, v10, v78
	v_mul_f32_e32 v79, v10, v79
	v_mul_f32_e32 v76, v10, v76
	v_mul_f32_e32 v77, v10, v77
	v_mul_f32_e32 v74, v10, v74
	v_mul_f32_e32 v75, v10, v75
	v_mul_f32_e32 v72, v10, v72
	v_mul_f32_e32 v73, v10, v73
	v_mul_f32_e32 v70, v10, v70
	v_mul_f32_e32 v71, v10, v71
	v_mul_f32_e32 v68, v10, v68
	v_mul_f32_e32 v69, v10, v69
	v_mul_f32_e32 v66, v10, v66
	v_mul_f32_e32 v67, v10, v67
	v_mul_f32_e32 v64, v10, v64
	v_mul_f32_e32 v65, v10, v65
	v_mul_f32_e32 v62, v10, v62
	v_mul_f32_e32 v63, v10, v63
	v_mul_f32_e32 v60, v10, v60
	v_mul_f32_e32 v61, v10, v61
	v_mul_f32_e32 v58, v10, v58
	v_mul_f32_e32 v59, v10, v59
	v_mul_f32_e32 v56, v10, v56
	v_mul_f32_e32 v57, v10, v57
	v_mul_f32_e32 v54, v10, v54
	v_mul_f32_e32 v55, v10, v55
	v_mul_f32_e32 v52, v10, v52
	v_mul_f32_e32 v53, v10, v53
	v_mul_f32_e32 v50, v10, v50
	v_mul_f32_e32 v51, v10, v51
	v_mul_f32_e32 v48, v10, v48
	v_mul_f32_e32 v49, v10, v49
	v_max3_f32 v10, v80, s18, v81
	v_max3_f32 v10, v10, v82, v83
	v_max3_f32 v10, v10, v84, v85
	v_max3_f32 v10, v10, v86, v87
	v_max3_f32 v10, v10, v88, v89
	v_max3_f32 v10, v10, v90, v91
	v_max3_f32 v10, v10, v92, v93
	v_max3_f32 v10, v10, v94, v95
	ds_bpermute_b32 v11, v209, v10
	v_mov_b32_e32 v232, v160
	s_waitcnt lgkmcnt(0)
	v_max3_f32 v161, v14, v10, v11
	v_sub_f32_e32 v11, v80, v161
	v_exp_f32_e32 v11, v11
	v_sub_f32_e32 v13, v81, v161
	v_sub_f32_e32 v10, v14, v161
	v_exp_f32_e32 v13, v13
	v_sub_f32_e32 v14, v82, v161
	v_exp_f32_e32 v14, v14
	v_sub_f32_e32 v80, v83, v161
	v_exp_f32_e32 v81, v80
	v_sub_f32_e32 v80, v84, v161
	v_add_f32_e32 v12, 0, v11
	v_exp_f32_e32 v82, v80
	v_sub_f32_e32 v80, v85, v161
	v_add_f32_e32 v12, v13, v12
	v_exp_f32_e32 v83, v80
	v_sub_f32_e32 v80, v86, v161
	v_add_f32_e32 v12, v14, v12
	v_exp_f32_e32 v85, v80
	v_sub_f32_e32 v80, v87, v161
	v_add_f32_e32 v12, v81, v12
	v_exp_f32_e32 v86, v80
	v_sub_f32_e32 v80, v88, v161
	v_add_f32_e32 v12, v82, v12
	v_exp_f32_e32 v87, v80
	v_sub_f32_e32 v80, v89, v161
	v_add_f32_e32 v12, v83, v12
	v_exp_f32_e32 v88, v80
	v_sub_f32_e32 v80, v90, v161
	v_add_f32_e32 v12, v85, v12
	v_exp_f32_e32 v89, v80
	v_sub_f32_e32 v80, v91, v161
	v_add_f32_e32 v12, v86, v12
	v_exp_f32_e32 v90, v80
	v_sub_f32_e32 v80, v92, v161
	v_add_f32_e32 v12, v87, v12
	v_exp_f32_e32 v91, v80
	v_sub_f32_e32 v80, v93, v161
	v_add_f32_e32 v12, v88, v12
	v_exp_f32_e32 v92, v80
	v_sub_f32_e32 v80, v94, v161
	v_add_f32_e32 v12, v89, v12
	v_exp_f32_e32 v93, v80
	v_sub_f32_e32 v80, v95, v161
	v_add_f32_e32 v12, v90, v12
	v_exp_f32_e32 v94, v80
	v_add_f32_e32 v12, v91, v12
	v_exp_f32_e32 v10, v10
	v_add_f32_e32 v12, v92, v12
	v_add_f32_e32 v12, v93, v12
	v_add_f32_e32 v84, v94, v12
	v_fmac_f32_e32 v84, v0, v10
	v_mul_f32_e32 v46, v10, v46
	v_mul_f32_e32 v47, v10, v47
	v_mul_f32_e32 v44, v10, v44
	v_mul_f32_e32 v45, v10, v45
	v_mul_f32_e32 v42, v10, v42
	v_mul_f32_e32 v43, v10, v43
	v_mul_f32_e32 v40, v10, v40
	v_mul_f32_e32 v41, v10, v41
	v_mul_f32_e32 v38, v10, v38
	v_mul_f32_e32 v39, v10, v39
	v_mul_f32_e32 v36, v10, v36
	v_mul_f32_e32 v37, v10, v37
	v_mul_f32_e32 v34, v10, v34
	v_mul_f32_e32 v35, v10, v35
	v_mul_f32_e32 v32, v10, v32
	v_mul_f32_e32 v33, v10, v33
	v_mul_f32_e32 v30, v10, v30
	v_mul_f32_e32 v31, v10, v31
	v_mul_f32_e32 v28, v10, v28
	v_mul_f32_e32 v29, v10, v29
	v_mul_f32_e32 v26, v10, v26
	v_mul_f32_e32 v27, v10, v27
	v_mul_f32_e32 v24, v10, v24
	v_mul_f32_e32 v25, v10, v25
	v_mul_f32_e32 v22, v10, v22
	v_mul_f32_e32 v23, v10, v23
	v_mul_f32_e32 v20, v10, v20
	v_mul_f32_e32 v21, v10, v21
	v_mul_f32_e32 v18, v10, v18
	v_mul_f32_e32 v19, v10, v19
	v_mul_f32_e32 v16, v10, v16
	v_mul_f32_e32 v17, v10, v17
	v_cvt_pk_bf16_f32 v80, v11, v13
	v_cvt_pk_bf16_f32 v82, v82, v83
	v_cvt_pk_bf16_f32 v83, v85, v86
	v_cvt_pk_bf16_f32 v10, v87, v88
	v_cvt_pk_bf16_f32 v11, v89, v90
	v_cvt_pk_bf16_f32 v12, v91, v92
	v_cvt_pk_bf16_f32 v13, v93, v94
	ds_read2_b64 v[86:89], v231 offset0:64 offset1:66
	ds_read2_b64 v[90:93], v231 offset0:68 offset1:70
	v_cvt_pk_bf16_f32 v81, v14, v81
	s_waitcnt lgkmcnt(1)
	v_mfma_f32_32x32x16_bf16 v[64:79], v[86:89], v[6:9], v[64:79]
	v_mov_b32_e32 v14, v161
	v_mov_b32_e32 v0, v84
	v_mfma_f32_32x32x16_bf16 v[32:47], v[86:89], v[80:83], v[32:47]
	ds_read2_b64 v[86:89], v15 offset0:128 offset1:130
	s_waitcnt lgkmcnt(0)
	v_mfma_f32_32x32x16_bf16 v[48:63], v[86:89], v[6:9], v[48:63]
	ds_read2_b64 v[6:9], v15 offset0:132 offset1:134
	s_waitcnt lgkmcnt(0)
	s_barrier
	v_mfma_f32_32x32x16_bf16 v[16:31], v[86:89], v[80:83], v[16:31]
	v_mfma_f32_32x32x16_bf16 v[64:79], v[90:93], v[2:5], v[64:79]
	v_mfma_f32_32x32x16_bf16 v[32:47], v[90:93], v[10:13], v[32:47]
	v_mfma_f32_32x32x16_bf16 v[48:63], v[6:9], v[2:5], v[48:63]
	v_mfma_f32_32x32x16_bf16 v[16:31], v[6:9], v[10:13], v[16:31]
	s_add_i32 s0, s64, -5
	s_cmp_ge_i32 s0, s56
	s_cbranch_scc1 .LBB0_332

.LBB0_378:
	s_nop 10
	v_max3_f32 v2, v80, s18, v81
	v_max3_f32 v2, v2, v82, v83
	v_max3_f32 v2, v2, v84, v85
	v_max3_f32 v2, v2, v86, v87
	v_max3_f32 v2, v2, v88, v89
	v_max3_f32 v2, v2, v90, v91
	v_max3_f32 v2, v2, v92, v93
	v_max3_f32 v2, v2, v94, v95
	ds_bpermute_b32 v3, v209, v2
	s_and_b64 vcc, exec, s[38:39]
	s_waitcnt lgkmcnt(0)
	v_max3_f32 v231, v234, v2, v3
	v_sub_f32_e32 v2, v80, v231
	v_exp_f32_e32 v15, v2
	v_sub_f32_e32 v2, v81, v231
	v_exp_f32_e32 v233, v2
	v_sub_f32_e32 v2, v82, v231
	v_exp_f32_e32 v235, v2
	v_sub_f32_e32 v2, v83, v231
	v_exp_f32_e32 v236, v2
	v_sub_f32_e32 v2, v84, v231
	v_exp_f32_e32 v237, v2
	v_sub_f32_e32 v2, v85, v231
	v_exp_f32_e32 v238, v2
	v_sub_f32_e32 v2, v86, v231
	v_exp_f32_e32 v239, v2
	v_sub_f32_e32 v2, v87, v231
	v_exp_f32_e32 v240, v2
	v_sub_f32_e32 v2, v88, v231
	v_exp_f32_e32 v241, v2
	v_sub_f32_e32 v2, v89, v231
	v_exp_f32_e32 v242, v2
	v_sub_f32_e32 v2, v90, v231
	v_exp_f32_e32 v243, v2
	v_sub_f32_e32 v2, v91, v231
	v_exp_f32_e32 v244, v2
	v_sub_f32_e32 v2, v92, v231
	v_exp_f32_e32 v245, v2
	v_sub_f32_e32 v2, v93, v231
	v_exp_f32_e32 v246, v2
	v_sub_f32_e32 v2, v94, v231
	v_exp_f32_e32 v247, v2
	v_sub_f32_e32 v2, v95, v231
	v_mfma_f32_32x32x16_bf16 v[80:95], v[168:171], v[112:115], 0
	v_exp_f32_e32 v248, v2
	v_cvt_pk_bf16_f32 v6, v15, v233
	v_cvt_pk_bf16_f32 v7, v235, v236
	v_cvt_pk_bf16_f32 v8, v237, v238
	v_cvt_pk_bf16_f32 v9, v239, v240
	v_cvt_pk_bf16_f32 v2, v241, v242
	v_cvt_pk_bf16_f32 v3, v243, v244
	v_mfma_f32_32x32x16_bf16 v[80:95], v[164:167], v[116:119], v[80:95]
	v_cvt_pk_bf16_f32 v4, v245, v246
	v_cvt_pk_bf16_f32 v5, v247, v248
	v_mfma_f32_32x32x16_bf16 v[80:95], v[10:13], v[120:123], v[80:95]
	v_mfma_f32_32x32x16_bf16 v[80:95], v[160:163], v[124:127], v[80:95]
	s_cbranch_vccnz .LBB0_381
	s_cmp_lt_i32 s3, s62
	s_cselect_b64 s[0:1], -1, 0
	s_cmp_gt_i32 s3, s55
	s_cselect_b64 s[26:27], -1, 0
	s_or_b64 s[0:1], s[0:1], s[26:27]
	s_andn2_b64 vcc, exec, s[0:1]
	s_cbranch_vccnz .LBB0_381
	s_sub_i32 s0, s2, s63
	v_add_u32_e32 v10, s0, v214
	v_cmp_lt_u32_e32 vcc, s66, v10
	v_add_u32_e32 v10, s0, v215
	s_nop 0
	v_cndmask_b32_e32 v80, v200, v80, vcc
	v_cmp_lt_u32_e32 vcc, s66, v10
	v_add_u32_e32 v10, s0, v216
	s_nop 0
	v_cndmask_b32_e32 v81, v200, v81, vcc
	v_cmp_lt_u32_e32 vcc, s66, v10
	v_add_u32_e32 v10, s0, v217
	s_nop 0
	v_cndmask_b32_e32 v82, v200, v82, vcc
	v_cmp_lt_u32_e32 vcc, s66, v10
	v_add_u32_e32 v10, s0, v218
	s_nop 0
	v_cndmask_b32_e32 v83, v200, v83, vcc
	v_cmp_lt_u32_e32 vcc, s66, v10
	v_add_u32_e32 v10, s0, v219
	s_nop 0
	v_cndmask_b32_e32 v84, v200, v84, vcc
	v_cmp_lt_u32_e32 vcc, s66, v10
	v_add_u32_e32 v10, s0, v220
	s_nop 0
	v_cndmask_b32_e32 v85, v200, v85, vcc
	v_cmp_lt_u32_e32 vcc, s66, v10
	v_add_u32_e32 v10, s0, v221
	s_nop 0
	v_cndmask_b32_e32 v86, v200, v86, vcc
	v_cmp_lt_u32_e32 vcc, s66, v10
	v_add_u32_e32 v10, s0, v222
	s_nop 0
	v_cndmask_b32_e32 v87, v200, v87, vcc
	v_cmp_lt_u32_e32 vcc, s66, v10
	v_add_u32_e32 v10, s0, v223
	s_nop 0
	v_cndmask_b32_e32 v88, v200, v88, vcc
	v_cmp_lt_u32_e32 vcc, s66, v10
	v_add_u32_e32 v10, s0, v224
	s_nop 0
	v_cndmask_b32_e32 v89, v200, v89, vcc
	v_cmp_lt_u32_e32 vcc, s66, v10
	v_add_u32_e32 v10, s0, v225
	s_nop 0
	v_cndmask_b32_e32 v90, v200, v90, vcc
	v_cmp_lt_u32_e32 vcc, s66, v10
	v_add_u32_e32 v10, s0, v226
	s_nop 0
	v_cndmask_b32_e32 v91, v200, v91, vcc
	v_cmp_lt_u32_e32 vcc, s66, v10
	v_add_u32_e32 v10, s0, v227
	s_nop 0
	v_cndmask_b32_e32 v92, v200, v92, vcc
	v_cmp_lt_u32_e32 vcc, s66, v10
	v_add_u32_e32 v10, s0, v228
	s_nop 0
	v_cndmask_b32_e32 v93, v200, v93, vcc
	v_cmp_lt_u32_e32 vcc, s66, v10
	v_add_u32_e32 v10, s0, v229
	s_nop 0
	v_cndmask_b32_e32 v94, v200, v94, vcc
	v_cmp_lt_u32_e32 vcc, s66, v10
	s_nop 1
	v_cndmask_b32_e32 v95, v200, v95, vcc
.LBB0_381:
	v_add_f32_e32 v11, 0, v15
	v_add_f32_e32 v11, v233, v11
	v_add_f32_e32 v11, v235, v11
	v_add_f32_e32 v11, v236, v11
	v_add_f32_e32 v11, v237, v11
	v_add_f32_e32 v11, v238, v11
	v_add_f32_e32 v11, v239, v11
	v_add_f32_e32 v11, v240, v11
	v_add_f32_e32 v11, v241, v11
	v_add_f32_e32 v11, v242, v11
	v_add_f32_e32 v11, v243, v11
	v_sub_f32_e32 v10, v234, v231
	v_add_f32_e32 v11, v244, v11
	v_add_f32_e32 v11, v245, v11
	v_exp_f32_e32 v10, v10
	v_add_f32_e32 v11, v246, v11
	v_add_f32_e32 v11, v247, v11
	v_add_f32_e32 v233, v248, v11
	v_fmac_f32_e32 v233, v232, v10
	v_mul_f32_e32 v78, v10, v78
	v_mul_f32_e32 v79, v10, v79
	v_mul_f32_e32 v76, v10, v76
	v_mul_f32_e32 v77, v10, v77
	v_mul_f32_e32 v74, v10, v74
	v_mul_f32_e32 v75, v10, v75
	v_mul_f32_e32 v72, v10, v72
	v_mul_f32_e32 v73, v10, v73
	v_mul_f32_e32 v70, v10, v70
	v_mul_f32_e32 v71, v10, v71
	v_mul_f32_e32 v68, v10, v68
	v_mul_f32_e32 v69, v10, v69
	v_mul_f32_e32 v66, v10, v66
	v_mul_f32_e32 v67, v10, v67
	v_mul_f32_e32 v64, v10, v64
	v_mul_f32_e32 v65, v10, v65
	v_mul_f32_e32 v62, v10, v62
	v_mul_f32_e32 v63, v10, v63
	v_mul_f32_e32 v60, v10, v60
	v_mul_f32_e32 v61, v10, v61
	v_mul_f32_e32 v58, v10, v58
	v_mul_f32_e32 v59, v10, v59
	v_mul_f32_e32 v56, v10, v56
	v_mul_f32_e32 v57, v10, v57
	v_mul_f32_e32 v54, v10, v54
	v_mul_f32_e32 v55, v10, v55
	v_mul_f32_e32 v52, v10, v52
	v_mul_f32_e32 v53, v10, v53
	v_mul_f32_e32 v50, v10, v50
	v_mul_f32_e32 v51, v10, v51
	v_mul_f32_e32 v48, v10, v48
	v_mul_f32_e32 v49, v10, v49
	v_max3_f32 v10, v80, s18, v81
	v_max3_f32 v10, v10, v82, v83
	v_max3_f32 v10, v10, v84, v85
	v_max3_f32 v10, v10, v86, v87
	v_max3_f32 v10, v10, v88, v89
	v_max3_f32 v10, v10, v90, v91
	v_max3_f32 v10, v10, v92, v93
	v_max3_f32 v10, v10, v94, v95
	ds_bpermute_b32 v11, v209, v10
	s_waitcnt lgkmcnt(0)
	v_max3_f32 v235, v14, v10, v11
	v_sub_f32_e32 v11, v80, v235
	v_exp_f32_e32 v11, v11
	v_sub_f32_e32 v13, v81, v235
	v_sub_f32_e32 v10, v14, v235
	v_exp_f32_e32 v13, v13
	v_sub_f32_e32 v14, v82, v235
	v_exp_f32_e32 v14, v14
	v_sub_f32_e32 v15, v83, v235
	v_exp_f32_e32 v81, v15
	v_sub_f32_e32 v15, v84, v235
	v_add_f32_e32 v12, 0, v11
	v_exp_f32_e32 v82, v15
	v_sub_f32_e32 v15, v85, v235
	v_add_f32_e32 v12, v13, v12
	v_exp_f32_e32 v83, v15
	v_sub_f32_e32 v15, v86, v235
	v_add_f32_e32 v12, v14, v12
	v_exp_f32_e32 v84, v15
	v_sub_f32_e32 v15, v87, v235
	v_add_f32_e32 v12, v81, v12
	v_exp_f32_e32 v85, v15
	v_sub_f32_e32 v15, v88, v235
	v_add_f32_e32 v12, v82, v12
	v_exp_f32_e32 v86, v15
	v_sub_f32_e32 v15, v89, v235
	v_add_f32_e32 v12, v83, v12
	v_exp_f32_e32 v87, v15
	v_sub_f32_e32 v15, v90, v235
	v_add_f32_e32 v12, v84, v12
	v_exp_f32_e32 v88, v15
	v_sub_f32_e32 v15, v91, v235
	v_add_f32_e32 v12, v85, v12
	v_exp_f32_e32 v89, v15
	v_sub_f32_e32 v15, v92, v235
	v_add_f32_e32 v12, v86, v12
	v_exp_f32_e32 v90, v15
	v_sub_f32_e32 v15, v93, v235
	v_add_f32_e32 v12, v87, v12
	v_exp_f32_e32 v91, v15
	v_sub_f32_e32 v15, v94, v235
	v_add_f32_e32 v12, v88, v12
	v_exp_f32_e32 v92, v15
	v_sub_f32_e32 v15, v95, v235
	v_add_f32_e32 v12, v89, v12
	v_exp_f32_e32 v93, v15
	v_add_f32_e32 v12, v90, v12
	v_exp_f32_e32 v10, v10
	v_add_f32_e32 v12, v91, v12
	v_add_f32_e32 v12, v92, v12
	v_add_f32_e32 v15, v93, v12
	v_fmac_f32_e32 v15, v0, v10
	v_add_u32_e32 v0, 0x3800, v230
	v_mul_f32_e32 v46, v10, v46
	v_mul_f32_e32 v47, v10, v47
	v_mul_f32_e32 v44, v10, v44
	v_mul_f32_e32 v45, v10, v45
	v_mul_f32_e32 v42, v10, v42
	v_mul_f32_e32 v43, v10, v43
	v_mul_f32_e32 v40, v10, v40
	v_mul_f32_e32 v41, v10, v41
	v_mul_f32_e32 v38, v10, v38
	v_mul_f32_e32 v39, v10, v39
	v_mul_f32_e32 v36, v10, v36
	v_mul_f32_e32 v37, v10, v37
	v_mul_f32_e32 v34, v10, v34
	v_mul_f32_e32 v35, v10, v35
	v_mul_f32_e32 v32, v10, v32
	v_mul_f32_e32 v33, v10, v33
	v_mul_f32_e32 v30, v10, v30
	v_mul_f32_e32 v31, v10, v31
	v_mul_f32_e32 v28, v10, v28
	v_mul_f32_e32 v29, v10, v29
	v_mul_f32_e32 v26, v10, v26
	v_mul_f32_e32 v27, v10, v27
	v_mul_f32_e32 v24, v10, v24
	v_mul_f32_e32 v25, v10, v25
	v_mul_f32_e32 v22, v10, v22
	v_mul_f32_e32 v23, v10, v23
	v_mul_f32_e32 v20, v10, v20
	v_mul_f32_e32 v21, v10, v21
	v_mul_f32_e32 v18, v10, v18
	v_mul_f32_e32 v19, v10, v19
	v_mul_f32_e32 v16, v10, v16
	v_mul_f32_e32 v17, v10, v17
	v_cvt_pk_bf16_f32 v80, v11, v13
	v_cvt_pk_bf16_f32 v82, v82, v83
	v_cvt_pk_bf16_f32 v83, v84, v85
	v_cvt_pk_bf16_f32 v10, v86, v87
	v_cvt_pk_bf16_f32 v11, v88, v89
	v_cvt_pk_bf16_f32 v12, v90, v91
	ds_read2_b64 v[84:87], v0 offset1:2
	ds_read2_b64 v[88:91], v0 offset0:4 offset1:6
	v_add_u32_e32 v0, 0x4000, v230
	v_cvt_pk_bf16_f32 v81, v14, v81
	s_waitcnt lgkmcnt(1)
	v_mfma_f32_32x32x16_bf16 v[64:79], v[84:87], v[6:9], v[64:79]
	v_cvt_pk_bf16_f32 v13, v92, v93
	v_mfma_f32_32x32x16_bf16 v[32:47], v[84:87], v[80:83], v[32:47]
	ds_read2_b64 v[84:87], v0 offset0:64 offset1:66
	s_waitcnt lgkmcnt(0)
	v_mfma_f32_32x32x16_bf16 v[48:63], v[84:87], v[6:9], v[48:63]
	ds_read2_b64 v[6:9], v0 offset0:68 offset1:70
	s_waitcnt lgkmcnt(0)
	s_barrier
	v_mfma_f32_32x32x16_bf16 v[16:31], v[84:87], v[80:83], v[16:31]
	v_mfma_f32_32x32x16_bf16 v[64:79], v[88:91], v[2:5], v[64:79]
	v_mfma_f32_32x32x16_bf16 v[32:47], v[88:91], v[10:13], v[32:47]
	v_mfma_f32_32x32x16_bf16 v[48:63], v[6:9], v[2:5], v[48:63]
	v_mfma_f32_32x32x16_bf16 v[16:31], v[6:9], v[10:13], v[16:31]
